# diff-attn K/V tile loads use SGPR base + 32-bit VGPR offsets (no per-iteration 64-bit VALU adds)
# speedup vs baseline: 1.0196x; 1.0034x over previous
; template <int NMAP, int VD, bool SWA> ...
;     ...
;     { const bf16_t* qr = Qp + (size_t)(16 * w + fr) * qpitch + fq * 8;
; #pragma unroll
;       for (int mp = 0; mp < NMAP; ++mp)
; #pragma unroll
;           for (int ks = 0; ks < 2; ++ks) qf[mp][ks] = *(const bf16x8*)(qr + mp * 64 + ks * 32); }
;     f32x4 oacc[NMAP][NET], negm[NMAP]; float mrun[NMAP], lsum[NMAP];
; #pragma unroll
;     for (int mp = 0; mp < NMAP; ++mp) { mrun[mp] = 0.f; lsum[mp] = 0.f; negm[mp] = (f32x4){0.f, 0.f, 0.f, 0.f};
; #pragma unroll
;         for (int et = 0; et < NET; ++et) oacc[mp][et] = (f32x4){0.f, 0.f, 0.f, 0.f}; }
;     const int ntiles = n0 + (t1hi - t1lo);
;     u32x4 kreg[NKC], vreg[NVC];
;     ...
;     ATT_LOAD(ATT_TILE(0));
;     ATT_STORE(0);
;     if (ntiles > 1) ATT_LOAD(ATT_TILE(1));
;     __syncthreads();
; __device__ __forceinline__ void mix_phase(const Args& a, LAS unsigned char* lds, int l, int tid_in, int G) {
;     ...
;         if (u < e3) {
;             const bool is_swa = (u >= e0 && u < e1) || (u >= e2);
;             const bool is_ctx = (u >= e1);
;             int b, hh, qb, row0;
;             if (u < e0) {
;                 const int v = u, x = v & 7, slot = (v >> 3) & 31, rnd = v >> 8, P = x * 4 + rnd * 2 + (slot >> 4);
;                 b = P >> 2; hh = P & 3; qb = slot & 15; row0 = b * SEQ + 128 * qb; }
;             else if (u < e1) { const int v = u - e0, x = v & 7, slot = (v >> 3) & 31, P = x * 2 + (slot >> 4); b = P >> 1; hh = P & 1; qb = slot & 15; row0 = b * SEQ + 128 * qb; }
;             else if (u < e2) { const int v = u - e1; b = v >> 3; hh = (v >> 1) & 3; qb = v & 1; row0 = T_LAT + b * CTXL + 128 * qb; }
;             else { const int v = u - e2; b = v >> 2; hh = (v >> 1) & 1; qb = v & 1; row0 = T_LAT + b * CTXL + 128 * qb; }
;             if (!is_swa) {
;                 attn_unit<2, 128, false>(lds, QB + (size_t)row0 * 512 + hh * 128, 512, KB + (size_t)(b * 4 + hh) * NKEY * 128, VBt + (size_t)(b * 4 + hh) * NKEY * 128,
;                                          is_ctx ? 4 : 36, 0, 0, 0, 0.f, lam, gsub, post_scale, O + (size_t)row0 * DM + 256 + hh * 128, tid);
.LBB0_121:
	s_and_b32 s0, s22, 0xffffff00
	s_cmpk_eq_i32 s0, 0x200
	s_cselect_b64 s[0:1], -1, 0
	s_cmp_ge_i32 s22, s13
	s_cselect_b64 s[8:9], -1, 0
	s_or_b64 s[10:11], s[8:9], s[0:1]
	s_cmpk_gt_i32 s22, 0x2ff
	s_mov_b64 s[8:9], -1
	s_cselect_b64 s[0:1], -1, 0
	s_and_b64 vcc, exec, s[10:11]
	v_ashrrev_i32_e32 v178, 31, v176
	v_lshlrev_b32_e32 v175, 2, v177
	s_cbranch_vccnz .LBB0_139
	s_ashr_i32 s21, s20, 31
	s_lshl_b64 s[8:9], s[20:21], 10
	v_readlane_b32 s3, v252, 43
	s_add_u32 s3, s3, s8
	v_readlane_b32 s8, v252, 44
	s_addc_u32 s8, s8, s9
	s_lshl_b32 s25, s16, 7
	s_lshl_b32 s9, s16, 8
	s_waitcnt vmcnt(0) lgkmcnt(0)
	v_add_u32_e32 v22, 0x200, v176
	s_add_u32 s28, s3, s9
	v_lshrrev_b32_e32 v0, 28, v178
	v_ashrrev_i32_e32 v23, 31, v22
	s_addc_u32 s29, s8, 0
	s_lshl_b32 s14, s24, 2
	v_add_u32_e32 v0, v176, v0
	v_lshrrev_b32_e32 v23, 28, v23
	s_add_i32 s14, s14, s16
	v_ashrrev_i32_e32 v34, 4, v0
	v_add_u32_e32 v23, v22, v23
	s_mul_i32 s8, s14, 0x90000
	v_readlane_b32 s9, v252, 47
	v_and_b32_e32 v0, -16, v0
	v_ashrrev_i32_e32 v35, 31, v34
	v_ashrrev_i32_e32 v36, 4, v23
	v_and_b32_e32 v23, -16, v23
	s_mul_hi_i32 s3, s14, 0x90000
	s_add_u32 s10, s9, s8
	v_readlane_b32 s9, v252, 48
	v_sub_u32_e32 v0, v176, v0
	v_lshlrev_b64 v[58:59], 8, v[34:35]
	v_sub_u32_e32 v35, v22, v23
	s_addc_u32 s11, s9, s3
	v_readlane_b32 s9, v252, 49
	v_ashrrev_i32_e32 v161, 31, v160
	v_lshlrev_b32_e32 v20, 3, v0
	v_ashrrev_i32_e32 v37, 31, v36
	v_lshlrev_b32_e32 v24, 3, v35
	s_add_u32 s8, s9, s8
	v_readlane_b32 s9, v252, 50
	v_lshlrev_b64 v[2:3], 10, v[160:161]
	v_ashrrev_i32_e32 v21, 31, v20
	v_lshlrev_b64 v[94:95], 8, v[36:37]
	v_ashrrev_i32_e32 v25, 31, v24
	s_addc_u32 s9, s9, s3
	v_lshl_add_u64 v[2:3], s[28:29], 0, v[2:3]
	v_mov_b32_e32 v163, v1
	v_lshl_add_u64 v[18:19], s[10:11], 0, v[58:59]
	v_lshlrev_b64 v[60:61], 1, v[20:21]
	v_lshl_add_u64 v[22:23], s[10:11], 0, v[94:95]
	v_lshlrev_b64 v[96:97], 1, v[24:25]
	v_lshl_add_u64 v[2:3], v[2:3], 0, v[162:163]
	v_lshl_add_u64 v[18:19], v[18:19], 0, v[60:61]
	v_lshl_add_u64 v[22:23], v[22:23], 0, v[96:97]
	v_lshl_add_u64 v[26:27], s[8:9], 0, v[58:59]
	global_load_dwordx4 v[14:17], v[2:3], off
	global_load_dwordx4 v[10:13], v[2:3], off offset:64
	global_load_dwordx4 v[6:9], v[2:3], off offset:128
	s_nop 0
	global_load_dwordx4 v[2:5], v[2:3], off offset:192
	v_lshl_add_u64 v[26:27], v[26:27], 0, v[60:61]
	global_load_dwordx4 v[18:21], v[18:19], off
	v_lshl_add_u64 v[30:31], s[8:9], 0, v[94:95]
	global_load_dwordx4 v[22:25], v[22:23], off
	v_lshl_add_u64 v[30:31], v[30:31], 0, v[96:97]
	global_load_dwordx4 v[26:29], v[26:27], off
	s_movk_i32 s15, 0x120
	global_load_dwordx4 v[30:33], v[30:31], off
	v_mul_lo_u32 v208, v34, s15
	v_lshlrev_b32_e32 v209, 4, v0
	v_mul_lo_u32 v210, v36, s15
	v_lshlrev_b32_e32 v211, 4, v35
	v_add3_u32 v34, 0, v208, v209
	v_add3_u32 v35, 0, v210, v211
	s_mov_b64 s[34:35], 0x4000
	v_lshlrev_b32_e32 v36, 2, v176
	v_and_b32_e32 v56, 12, v36
	v_mbcnt_hi_u32_b32 v36, -1, v190
	v_and_b32_e32 v38, 64, v36
	v_xor_b32_e32 v37, 16, v36
	v_add_u32_e32 v38, 64, v38
	v_cmp_lt_i32_e32 vcc, v37, v38
	v_mul_u32_u24_e32 v182, 0x120, v173
	v_add3_u32 v57, 0, v162, v182
	v_cndmask_b32_e32 v37, v36, v37, vcc
	v_lshlrev_b32_e32 v179, 2, v37
	v_xor_b32_e32 v37, 32, v36
	v_cmp_lt_i32_e32 vcc, v37, v38
	v_readlane_b32 s28, v254, 39
	v_readlane_b32 s29, v254, 40
	v_cndmask_b32_e32 v36, v36, v37, vcc
	v_lshlrev_b32_e32 v180, 2, v36
	v_lshlrev_b32_e32 v163, 2, v177
	v_bfe_u32 v0, v176, 2, 2
	s_mov_b32 s26, s28
	v_readlane_b32 s28, v254, 43
	v_or_b32_e32 v0, v163, v0
	v_readlane_b32 s29, v254, 44
	v_lshlrev_b32_e32 v107, 3, v177
	s_mov_b32 s3, 1
	v_mul_u32_u24_e32 v0, 0x120, v0
	s_waitcnt vmcnt(3)
	ds_write_b128 v34, v[18:21]
	s_waitcnt vmcnt(2)
	ds_write_b128 v35, v[22:25]
	s_waitcnt vmcnt(1)
	ds_write_b128 v34, v[26:29] offset:18432
	s_waitcnt vmcnt(0)
	ds_write_b128 v35, v[30:33] offset:18432
	v_lshl_add_u64 v[26:27], v[58:59], 0, s[34:35]
	v_lshl_add_u64 v[18:19], s[10:11], 0, v[26:27]
	v_lshl_add_u64 v[30:31], v[94:95], 0, s[34:35]
	v_lshl_add_u64 v[18:19], v[18:19], 0, v[60:61]
	v_lshl_add_u64 v[22:23], s[10:11], 0, v[30:31]
	global_load_dwordx4 v[18:21], v[18:19], off
	v_lshl_add_u64 v[22:23], v[22:23], 0, v[96:97]
	v_lshl_add_u64 v[26:27], s[8:9], 0, v[26:27]
	global_load_dwordx4 v[22:25], v[22:23], off
	v_lshl_add_u64 v[26:27], v[26:27], 0, v[60:61]
	v_lshl_add_u64 v[30:31], s[8:9], 0, v[30:31]
	global_load_dwordx4 v[26:29], v[26:27], off
	v_lshl_add_u64 v[30:31], v[30:31], 0, v[96:97]
	global_load_dwordx4 v[30:33], v[30:31], off
	s_mov_b64 s[34:35], 0x8000
	s_waitcnt lgkmcnt(0)
	s_barrier
; #define LAS __attribute__((address_space(3)))
; template <int NMAP, int VD, bool SWA> ...
;     ...
;     for (int i = 0; i < ntiles; ++i) {
;         const int t = ATT_TILE(i);
;         if (i + 1 < ntiles) { ATT_STORE((i + 1) & 1); if (i + 2 < ntiles) ATT_LOAD(ATT_TILE(i + 2)); }
;         const LAS bf16_t* kS = (const LAS bf16_t*)(lds + (i & 1) * BUFB);
;         const LAS bf16_t* vS = (const LAS bf16_t*)(lds + (i & 1) * BUFB + KBYTES);
;         bf16x8 pf[NMAP][2];
;         f32x4 sacc[NMAP][4];
; #pragma unroll
;         for (int mp = 0; mp < NMAP; ++mp) {
;             bf16x8 kf[4][2];
; #pragma unroll
;             for (int kt = 0; kt < 4; ++kt)
; #pragma unroll
;                 for (int ks = 0; ks < 2; ++ks) kf[kt][ks] = *(const LAS bf16x8*)(kS + (16 * kt + fr) * KP + mp * KMS + ks * 32 + fq * 8);
;             __builtin_amdgcn_sched_barrier(0);
; #pragma unroll
;             for (int kt = 0; kt < 4; ++kt) sacc[mp][kt] = __builtin_amdgcn_mfma_f32_16x16x32_bf16(kf[kt][0], qf[mp][0], negm[mp], 0, 0, 0);
; #pragma unroll
;             for (int kt = 0; kt < 4; ++kt) sacc[mp][kt] = __builtin_amdgcn_mfma_f32_16x16x32_bf16(kf[kt][1], qf[mp][1], sacc[mp][kt], 0, 0, 0);
;         }
;         bf16x8 va[4];
;     ...
; #pragma unroll
;         for (int i2 = 0; i2 < 4; ++i2) ATT_LDV(va[i2], i2);
;         if (SWA && t >= 4) {
;             const int dq = qp0 + 16 * w + fr - (64 * (t - 4) + 4 * fq);
; #pragma unroll
;             for (int kt = 0; kt < 4; ++kt)
; #pragma unroll
;                 for (int r = 0; r < 4; ++r) { const int d = dq - 16 * kt - r; if (d > 128 || d < -128) {
; #pragma unroll
;                     for (int mp = 0; mp < NMAP; ++mp) sacc[mp][kt][r] = -INFINITY; } }
;         }
;         float mx[NMAP];
; #pragma unroll
;         for (int mp = 0; mp < NMAP; ++mp) {
;             float v = fmax2(fmax2(sacc[mp][0][0], sacc[mp][0][1]), fmax2(sacc[mp][0][2], sacc[mp][0][3]));
; #pragma unroll
;             for (int kt = 1; kt < 4; ++kt) v = fmax2(v, fmax2(fmax2(sacc[mp][kt][0], sacc[mp][kt][1]), fmax2(sacc[mp][kt][2], sacc[mp][kt][3])));
;             mx[mp] = v;
;         }
; #pragma unroll
;         for (int mp = 0; mp < NMAP; ++mp) mx[mp] = fmax2(mx[mp], __shfl_xor(mx[mp], 16));
; #pragma unroll
;         for (int mp = 0; mp < NMAP; ++mp) mx[mp] = fmax2(mx[mp], __shfl_xor(mx[mp], 32));
; #pragma unroll
;         for (int mp = 0; mp < NMAP; ++mp) {
	s_waitcnt vmcnt(3)
	ds_write_b128 v34, v[18:21] offset:36864
	s_waitcnt vmcnt(2)
	ds_write_b128 v35, v[22:25] offset:36864
	s_waitcnt vmcnt(1)
	ds_write_b128 v34, v[26:29] offset:55296
	s_waitcnt vmcnt(0)
	ds_write_b128 v35, v[30:33] offset:55296
	v_lshl_add_u64 v[18:19], v[58:59], 0, s[34:35]
	v_lshl_add_u64 v[20:21], s[10:11], 0, v[18:19]
	v_lshl_add_u64 v[18:19], s[8:9], 0, v[18:19]
	v_lshl_add_u64 v[20:21], v[20:21], 0, v[60:61]
	v_lshl_add_u64 v[18:19], v[18:19], 0, v[60:61]
	global_load_dwordx4 v[86:89], v[20:21], off
	global_load_dwordx4 v[98:101], v[18:19], off
	v_lshl_add_u64 v[20:21], v[94:95], 0, s[34:35]
	v_lshl_add_u64 v[22:23], s[10:11], 0, v[20:21]
	v_lshl_add_u64 v[18:19], s[8:9], 0, v[20:21]
	v_lshl_add_u64 v[22:23], v[22:23], 0, v[96:97]
	v_lshl_add_u64 v[18:19], v[18:19], 0, v[96:97]
	global_load_dwordx4 v[90:93], v[22:23], off
	global_load_dwordx4 v[102:105], v[18:19], off
	ds_read_b128 v[18:21], v57
	ds_read_b128 v[22:25], v57 offset:64
	ds_read_b128 v[26:29], v57 offset:4608
	ds_read_b128 v[30:33], v57 offset:4672
	ds_read_b128 v[34:37], v57 offset:9216
	ds_read_b128 v[38:41], v57 offset:9280
	ds_read_b128 v[42:45], v57 offset:13824
	ds_read_b128 v[46:49], v57 offset:13888
	s_waitcnt lgkmcnt(7)
	v_mfma_f32_16x16x32_bf16 v[18:21], v[18:21], v[14:17], 0
	s_waitcnt lgkmcnt(5)
	v_mfma_f32_16x16x32_bf16 v[26:29], v[26:29], v[14:17], 0
	s_waitcnt lgkmcnt(3)
	v_mfma_f32_16x16x32_bf16 v[34:37], v[34:37], v[14:17], 0
	s_waitcnt lgkmcnt(1)
	v_mfma_f32_16x16x32_bf16 v[42:45], v[42:45], v[14:17], 0
	v_mfma_f32_16x16x32_bf16 v[18:21], v[22:25], v[10:13], v[18:21]
	v_mfma_f32_16x16x32_bf16 v[24:27], v[30:33], v[10:13], v[26:29]
	v_mfma_f32_16x16x32_bf16 v[28:31], v[38:41], v[10:13], v[34:37]
	s_waitcnt lgkmcnt(0)
	v_mfma_f32_16x16x32_bf16 v[32:35], v[46:49], v[10:13], v[42:45]
	s_nop 0
	ds_read_b128 v[36:39], v57 offset:128
	s_nop 0
	ds_read_b128 v[40:43], v57 offset:192
	ds_read_b128 v[44:47], v57 offset:4736
	ds_read_b128 v[48:51], v57 offset:4800
	ds_read_b128 v[52:55], v57 offset:9344
	ds_read_b128 v[62:65], v57 offset:9408
	ds_read_b128 v[66:69], v57 offset:13952
	ds_read_b128 v[70:73], v57 offset:14016
	v_lshlrev_b32_e32 v181, 1, v56
	v_med3_f32 v23, v18, v19, s27
	v_med3_f32 v56, v20, v21, s27
	s_waitcnt lgkmcnt(7)
	v_mfma_f32_16x16x32_bf16 v[36:39], v[36:39], v[6:9], 0
	v_med3_f32 v23, v23, v56, s27
	v_med3_f32 v56, v24, v25, s27
	v_med3_f32 v57, v26, v27, s27
	v_med3_f32 v56, v56, v57, s27
	s_waitcnt lgkmcnt(5)
	v_mfma_f32_16x16x32_bf16 v[44:47], v[44:47], v[6:9], 0
	v_med3_f32 v23, v23, v56, s27
	v_med3_f32 v56, v28, v29, s27
	v_med3_f32 v57, v30, v31, s27
	v_med3_f32 v56, v56, v57, s27
	v_med3_f32 v23, v23, v56, s27
	v_med3_f32 v56, v32, v33, s27
	v_mfma_f32_16x16x32_bf16 v[36:39], v[40:43], v[2:5], v[36:39]
	v_med3_f32 v40, v34, v35, s27
	v_med3_f32 v40, v56, v40, s27
	v_med3_f32 v23, v23, v40, s27
	s_waitcnt lgkmcnt(3)
	v_mfma_f32_16x16x32_bf16 v[52:55], v[52:55], v[6:9], 0
	v_add3_u32 v22, 0, v0, v181
	v_mad_i64_i32 v[58:59], s[8:9], s14, v192, v[58:59]
	v_mfma_f32_16x16x32_bf16 v[40:43], v[48:51], v[2:5], v[44:47]
	v_lshl_add_u64 v[58:59], v[58:59], 0, v[60:61]
	s_and_b64 s[8:9], s[0:1], exec
	s_cselect_b32 s10, 1, 33
	s_waitcnt lgkmcnt(1)
	v_mfma_f32_16x16x32_bf16 v[66:69], v[66:69], v[6:9], 0
	v_med3_f32 v44, v36, v37, s27
	v_med3_f32 v45, v38, v39, s27
	v_med3_f32 v56, v44, v45, s27
	v_mfma_f32_16x16x32_bf16 v[44:47], v[62:65], v[2:5], v[52:55]
	v_med3_f32 v48, v40, v41, s27
	v_med3_f32 v49, v42, v43, s27
	s_lshl_b32 s11, s10, 14
	v_med3_f32 v52, v48, v49, s27
	s_waitcnt lgkmcnt(0)
	v_mfma_f32_16x16x32_bf16 v[48:51], v[70:73], v[2:5], v[66:69]
	s_nop 1
	v_med3_f32 v53, v44, v45, s27
	v_med3_f32 v54, v46, v47, s27
	v_med3_f32 v52, v56, v52, s27
	v_med3_f32 v53, v53, v54, s27
	v_med3_f32 v52, v52, v53, s27
	s_nop 0
	v_med3_f32 v53, v48, v49, s27
	v_med3_f32 v54, v50, v51, s27
	v_med3_f32 v53, v53, v54, s27
	v_med3_f32 v54, v52, v53, s27
	ds_bpermute_b32 v55, v179, v23
	ds_bpermute_b32 v56, v179, v54
	ds_read_b64_tr_b16 v[52:53], v22 offset:18432
	ds_read_b64_tr_b16 v[62:63], v22 offset:18464
	ds_read_b64_tr_b16 v[66:67], v22 offset:18496
	ds_read_b64_tr_b16 v[70:71], v22 offset:18528
	s_waitcnt lgkmcnt(5)
	v_med3_f32 v23, v23, v55, s27
	s_waitcnt lgkmcnt(4)
	v_med3_f32 v56, v54, v56, s27
	ds_bpermute_b32 v57, v180, v23
	ds_bpermute_b32 v74, v180, v56
	ds_read_b64_tr_b16 v[54:55], v22 offset:23040
	ds_read_b64_tr_b16 v[64:65], v22 offset:23072
	ds_read_b64_tr_b16 v[68:69], v22 offset:23104
	ds_read_b64_tr_b16 v[72:73], v22 offset:23136
	s_waitcnt lgkmcnt(5)
	v_med3_f32 v23, v23, v57, s27
	s_waitcnt lgkmcnt(4)
	v_med3_f32 v109, v56, v74, s27
	v_sub_f32_e32 v35, v35, v23
	v_sub_f32_e32 v34, v34, v23
	v_sub_f32_e32 v33, v33, v23
	v_sub_f32_e32 v32, v32, v23
	v_sub_f32_e32 v31, v31, v23
	v_sub_f32_e32 v30, v30, v23
	v_sub_f32_e32 v29, v29, v23
	v_sub_f32_e32 v28, v28, v23
	v_sub_f32_e32 v27, v27, v23
	v_sub_f32_e32 v26, v26, v23
	v_sub_f32_e32 v25, v25, v23
	v_sub_f32_e32 v24, v24, v23
	v_sub_f32_e32 v21, v21, v23
	v_sub_f32_e32 v20, v20, v23
	v_sub_f32_e32 v19, v19, v23
	v_sub_f32_e32 v18, v18, v23
	v_exp_f32_e32 v111, v28
	v_exp_f32_e32 v156, v29
	v_exp_f32_e32 v157, v30
	v_exp_f32_e32 v164, v31
	v_exp_f32_e32 v165, v32
	v_exp_f32_e32 v166, v33
	v_exp_f32_e32 v167, v34
	v_exp_f32_e32 v183, v35
	v_sub_f32_e32 v28, v43, v109
	v_sub_f32_e32 v29, v42, v109
	v_sub_f32_e32 v30, v41, v109
	v_sub_f32_e32 v31, v40, v109
	v_sub_f32_e32 v32, v39, v109
	v_sub_f32_e32 v33, v38, v109
	v_sub_f32_e32 v34, v37, v109
	v_sub_f32_e32 v35, v36, v109
	v_exp_f32_e32 v56, v18
	v_exp_f32_e32 v57, v19
	v_exp_f32_e32 v74, v20
	v_exp_f32_e32 v75, v21
	v_exp_f32_e32 v76, v24
	v_exp_f32_e32 v106, v25
	v_exp_f32_e32 v108, v26
	v_exp_f32_e32 v110, v27
	v_cvt_pk_bf16_f32 v24, v56, v57
	v_cvt_pk_bf16_f32 v25, v74, v75
	v_cvt_pk_bf16_f32 v26, v76, v106
	v_cvt_pk_bf16_f32 v27, v108, v110
	v_cvt_pk_bf16_f32 v18, v111, v156
	v_cvt_pk_bf16_f32 v19, v157, v164
	v_cvt_pk_bf16_f32 v20, v165, v166
	v_cvt_pk_bf16_f32 v21, v167, v183
	v_sub_f32_e32 v77, v51, v109
	v_sub_f32_e32 v78, v50, v109
	v_sub_f32_e32 v79, v49, v109
	v_exp_f32_e32 v202, v35
	v_exp_f32_e32 v203, v34
	v_exp_f32_e32 v212, v33
	v_exp_f32_e32 v213, v32
	v_exp_f32_e32 v214, v31
	v_exp_f32_e32 v215, v30
	v_exp_f32_e32 v216, v29
	v_exp_f32_e32 v217, v28
	v_cvt_pk_bf16_f32 v28, v202, v203
	s_waitcnt lgkmcnt(3)
; __device__ __forceinline__ unsigned cvt_pk_bf16(float lo, float hi) { unsigned r; asm volatile("v_cvt_pk_bf16_f32 %0, %1, %2" : "=v"(r) : "v"(lo), "v"(hi)); return r; }
; template <int NMAP, int VD, bool SWA> ...
;     ...
;             float ps = 0.f;
; #pragma unroll
;             for (int kt = 0; kt < 4; ++kt)
; #pragma unroll
;                 for (int r = 0; r < 4; ++r) { const float p = __builtin_amdgcn_exp2f(sacc[mp][kt][r]); sacc[mp][kt][r] = p; ps += p; }
;             lsum[mp] += ps;
; #pragma unroll
;             for (int s2 = 0; s2 < 2; ++s2) {
;                 u32x4 pk; pk.x = cvt_pk_bf16(sacc[mp][2 * s2][0], sacc[mp][2 * s2][1]); pk.y = cvt_pk_bf16(sacc[mp][2 * s2][2], sacc[mp][2 * s2][3]);
;                 pk.z = cvt_pk_bf16(sacc[mp][2 * s2 + 1][0], sacc[mp][2 * s2 + 1][1]); pk.w = cvt_pk_bf16(sacc[mp][2 * s2 + 1][2], sacc[mp][2 * s2 + 1][3]);
;                 pf[mp][s2] = __builtin_bit_cast(bf16x8, pk);
;             }
;         }
; #pragma unroll
;         for (int idx = 0; idx < 2 * NET; ++idx) {
;             const int et = idx % NET, s2 = idx / NET;
;             const bf16x8 cur = va[idx & 3];
;             if (idx + 4 < 2 * NET) ATT_LDV(va[idx & 3], idx + 4);
; #pragma unroll
;             for (int mp = 0; mp < NMAP; ++mp) oacc[mp][et] = __builtin_amdgcn_mfma_f32_16x16x32_bf16(cur, pf[mp][s2], oacc[mp][et], 0, 0, 0);
;         }
	v_mfma_f32_16x16x32_bf16 v[32:35], v[52:55], v[24:27], 0
	v_cvt_pk_bf16_f32 v29, v212, v213
	v_cvt_pk_bf16_f32 v30, v214, v215
	v_cvt_pk_bf16_f32 v31, v216, v217
	v_sub_f32_e32 v49, v46, v109
	v_mfma_f32_16x16x32_bf16 v[36:39], v[52:55], v[28:31], 0
	v_sub_f32_e32 v52, v48, v109
	v_sub_f32_e32 v48, v47, v109
	v_sub_f32_e32 v50, v45, v109
	v_sub_f32_e32 v44, v44, v109
	s_waitcnt lgkmcnt(2)
	v_mfma_f32_16x16x32_bf16 v[40:43], v[62:65], v[24:27], 0
	v_exp_f32_e32 v218, v44
	v_exp_f32_e32 v219, v50
	v_exp_f32_e32 v220, v49
	v_mfma_f32_16x16x32_bf16 v[44:47], v[62:65], v[28:31], 0
	v_exp_f32_e32 v221, v48
	v_exp_f32_e32 v222, v52
	v_exp_f32_e32 v223, v79
	v_exp_f32_e32 v224, v78
	v_exp_f32_e32 v225, v77
	v_cvt_pk_bf16_f32 v112, v218, v219
	v_cvt_pk_bf16_f32 v113, v220, v221
	v_cvt_pk_bf16_f32 v114, v222, v223
	v_cvt_pk_bf16_f32 v115, v224, v225
	ds_read_b64_tr_b16 v[64:65], v22 offset:23168
	ds_read_b64_tr_b16 v[62:63], v22 offset:18560
	s_waitcnt lgkmcnt(3)
	v_mfma_f32_16x16x32_bf16 v[48:51], v[66:69], v[24:27], 0
	v_mfma_f32_16x16x32_bf16 v[52:55], v[66:69], v[28:31], 0
	ds_read_b64_tr_b16 v[68:69], v22 offset:23200
	ds_read_b64_tr_b16 v[66:67], v22 offset:18592
	s_waitcnt lgkmcnt(2)
	v_mfma_f32_16x16x32_bf16 v[124:127], v[62:65], v[24:27], 0
	v_mfma_f32_16x16x32_bf16 v[128:131], v[62:65], v[28:31], 0
	ds_read_b64_tr_b16 v[62:63], v22 offset:18624
	ds_read_b64_tr_b16 v[64:65], v22 offset:23232
	s_waitcnt lgkmcnt(2)
	v_mfma_f32_16x16x32_bf16 v[132:135], v[66:69], v[24:27], 0
	v_mfma_f32_16x16x32_bf16 v[136:139], v[66:69], v[28:31], 0
	ds_read_b64_tr_b16 v[66:67], v22 offset:18656
	s_waitcnt lgkmcnt(1)
	v_mfma_f32_16x16x32_bf16 v[140:143], v[62:65], v[24:27], 0
	v_mfma_f32_16x16x32_bf16 v[144:147], v[62:65], v[28:31], 0
	ds_read_b64_tr_b16 v[68:69], v22 offset:23264
	ds_read_b64_tr_b16 v[62:63], v22 offset:27648
	v_mfma_f32_16x16x32_bf16 v[116:119], v[70:73], v[24:27], 0
	s_waitcnt lgkmcnt(1)
	v_mfma_f32_16x16x32_bf16 v[148:151], v[66:69], v[24:27], 0
	ds_read_b64_tr_b16 v[64:65], v22 offset:32256
	ds_read_b64_tr_b16 v[24:25], v22 offset:27680
	ds_read_b64_tr_b16 v[152:153], v22 offset:27712
	s_waitcnt lgkmcnt(2)
	v_mfma_f32_16x16x32_bf16 v[78:81], v[62:65], v[18:21], v[32:35]
	s_nop 2
	v_add_f32_e32 v32, 0, v56
	v_add_f32_e32 v32, v57, v32
	v_add_f32_e32 v32, v74, v32
	v_add_f32_e32 v32, v75, v32
	v_mfma_f32_16x16x32_bf16 v[120:123], v[70:73], v[28:31], 0
	v_add_f32_e32 v32, v76, v32
	v_add_f32_e32 v32, v106, v32
	v_add_f32_e32 v32, v108, v32
	v_mfma_f32_16x16x32_bf16 v[168:171], v[66:69], v[28:31], 0
	ds_read_b64_tr_b16 v[28:29], v22 offset:27744
	ds_read_b64_tr_b16 v[26:27], v22 offset:32288
	ds_read_b64_tr_b16 v[154:155], v22 offset:32320
	ds_read_b64_tr_b16 v[30:31], v22 offset:32352
	v_add_f32_e32 v32, v110, v32
	s_waitcnt lgkmcnt(2)
	v_mfma_f32_16x16x32_bf16 v[74:77], v[24:27], v[18:21], v[40:43]
	v_mfma_f32_16x16x32_bf16 v[70:73], v[24:27], v[112:115], v[44:47]
	v_add_f32_e32 v24, v111, v32
	v_add_f32_e32 v24, v156, v24
	v_add_f32_e32 v24, v157, v24
	v_add_f32_e32 v24, v164, v24
	v_add_f32_e32 v24, v165, v24
	v_add_f32_e32 v24, v166, v24
	v_mfma_f32_16x16x32_bf16 v[82:85], v[62:65], v[112:115], v[36:39]
	s_nop 2
	v_add_f32_e32 v36, v167, v24
	s_waitcnt lgkmcnt(1)
	v_mfma_f32_16x16x32_bf16 v[66:69], v[152:155], v[18:21], v[48:51]
	ds_read_b64_tr_b16 v[24:25], v22 offset:27776
	ds_read_b64_tr_b16 v[26:27], v22 offset:32384
	v_mfma_f32_16x16x32_bf16 v[62:65], v[152:155], v[112:115], v[52:55]
	s_waitcnt lgkmcnt(2)
	v_mfma_f32_16x16x32_bf16 v[54:57], v[28:31], v[18:21], v[116:119]
	ds_read_b64_tr_b16 v[32:33], v22 offset:27808
	s_nop 1
	ds_read_b64_tr_b16 v[116:117], v22 offset:27840
	ds_read_b64_tr_b16 v[152:153], v22 offset:27872
	ds_read_b64_tr_b16 v[34:35], v22 offset:32416
	ds_read_b64_tr_b16 v[118:119], v22 offset:32448
	ds_read_b64_tr_b16 v[154:155], v22 offset:32480
	v_add_f32_e32 v22, v183, v36
	v_pk_add_f32 v[166:167], v[22:23], 0 op_sel_hi:[1,0]
	v_add_f32_e32 v22, 0, v202
	v_add_f32_e32 v22, v203, v22
	v_add_f32_e32 v22, v212, v22
	v_add_f32_e32 v22, v213, v22
	v_add_f32_e32 v22, v214, v22
	v_add_f32_e32 v22, v215, v22
	v_add_f32_e32 v22, v216, v22
	v_add_f32_e32 v22, v217, v22
	v_add_f32_e32 v22, v218, v22
	v_add_f32_e32 v22, v219, v22
	v_add_f32_e32 v22, v220, v22
	v_add_f32_e32 v22, v221, v22
	v_add_f32_e32 v22, v222, v22
	v_add_f32_e32 v22, v223, v22
	v_add_f32_e32 v108, v224, v22
	v_mfma_f32_16x16x32_bf16 v[50:53], v[28:31], v[112:115], v[120:123]
	v_add_f32_e32 v108, v225, v108
	v_pk_add_f32 v[164:165], v[108:109], 0 op_sel_hi:[1,0]
	v_xor_b32_e32 v106, 0x80000000, v167
	s_waitcnt lgkmcnt(6)
	v_mfma_f32_16x16x32_bf16 v[46:49], v[24:27], v[18:21], v[124:127]
	v_xor_b32_e32 v110, 0x80000000, v165
	v_lshlrev_b32_e32 v183, 1, v107
	v_mov_b32_e32 v111, v110
	v_mfma_f32_16x16x32_bf16 v[42:45], v[24:27], v[112:115], v[128:131]
	v_mov_b32_e32 v107, v106
	v_mov_b32_e32 v108, v106
	v_mov_b32_e32 v109, v106
	s_waitcnt lgkmcnt(2)
	v_mfma_f32_16x16x32_bf16 v[38:41], v[32:35], v[18:21], v[132:135]
	s_waitcnt lgkmcnt(0)
	s_barrier
	v_mfma_f32_16x16x32_bf16 v[34:37], v[32:35], v[112:115], v[136:139]
	v_mfma_f32_16x16x32_bf16 v[30:33], v[116:119], v[18:21], v[140:143]
	v_mfma_f32_16x16x32_bf16 v[26:29], v[116:119], v[112:115], v[144:147]
	v_mfma_f32_16x16x32_bf16 v[22:25], v[152:155], v[18:21], v[148:151]
	v_mfma_f32_16x16x32_bf16 v[18:21], v[152:155], v[112:115], v[168:171]
	v_mov_b32_e32 v112, v110
	v_mov_b32_e32 v113, v110
	s_nop 0
	v_lshl_add_u64 v[168:169], s[4:5], 0, v[58:59]
	v_mad_i64_i32 v[58:59], s[8:9], s14, v192, v[94:95]
	v_lshl_add_u64 v[58:59], v[58:59], 0, v[96:97]
	v_lshl_add_u64 v[170:171], s[4:5], 0, v[58:59]
	s_mov_b64 s[8:9], 0
	v_subrev_u32_e32 v236, s4, v168
	v_subrev_u32_e32 v237, s4, v170
	v_add_u32_e32 v238, 0x1200000, v236
	v_add_u32_e32 v239, 0x1200000, v237
	s_add_u32 s34, s4, 0x1810c000
	s_addc_u32 s35, s5, 0
	s_branch .LBB0_125

; #define LAS __attribute__((address_space(3)))
; template <int NMAP, int VD, bool SWA> ...
;     ...
;     for (int i = 0; i < ntiles; ++i) {
;         const int t = ATT_TILE(i);
;         if (i + 1 < ntiles) { ATT_STORE((i + 1) & 1); if (i + 2 < ntiles) ATT_LOAD(ATT_TILE(i + 2)); }
;         const LAS bf16_t* kS = (const LAS bf16_t*)(lds + (i & 1) * BUFB);
;         const LAS bf16_t* vS = (const LAS bf16_t*)(lds + (i & 1) * BUFB + KBYTES);
;         bf16x8 pf[NMAP][2];
;         f32x4 sacc[NMAP][4];
; #pragma unroll
;         for (int mp = 0; mp < NMAP; ++mp) {
;             bf16x8 kf[4][2];
; #pragma unroll
;             for (int kt = 0; kt < 4; ++kt)
; #pragma unroll
;                 for (int ks = 0; ks < 2; ++ks) kf[kt][ks] = *(const LAS bf16x8*)(kS + (16 * kt + fr) * KP + mp * KMS + ks * 32 + fq * 8);
;             __builtin_amdgcn_sched_barrier(0);
; #pragma unroll
;             for (int kt = 0; kt < 4; ++kt) sacc[mp][kt] = __builtin_amdgcn_mfma_f32_16x16x32_bf16(kf[kt][0], qf[mp][0], negm[mp], 0, 0, 0);
; #pragma unroll
;             for (int kt = 0; kt < 4; ++kt) sacc[mp][kt] = __builtin_amdgcn_mfma_f32_16x16x32_bf16(kf[kt][1], qf[mp][1], sacc[mp][kt], 0, 0, 0);
;         }
;         bf16x8 va[4];
;     ...
; #pragma unroll
;         for (int i2 = 0; i2 < 4; ++i2) ATT_LDV(va[i2], i2);
;         if (SWA && t >= 4) {
;             const int dq = qp0 + 16 * w + fr - (64 * (t - 4) + 4 * fq);
; #pragma unroll
;             for (int kt = 0; kt < 4; ++kt)
; #pragma unroll
;                 for (int r = 0; r < 4; ++r) { const int d = dq - 16 * kt - r; if (d > 128 || d < -128) {
; #pragma unroll
;                     for (int mp = 0; mp < NMAP; ++mp) sacc[mp][kt][r] = -INFINITY; } }
;         }
;         float mx[NMAP];
; #pragma unroll
;         for (int mp = 0; mp < NMAP; ++mp) {
;             float v = fmax2(fmax2(sacc[mp][0][0], sacc[mp][0][1]), fmax2(sacc[mp][0][2], sacc[mp][0][3]));
; #pragma unroll
;             for (int kt = 1; kt < 4; ++kt) v = fmax2(v, fmax2(fmax2(sacc[mp][kt][0], sacc[mp][kt][1]), fmax2(sacc[mp][kt][2], sacc[mp][kt][3])));
;             mx[mp] = v;
;         }
; #pragma unroll
;         for (int mp = 0; mp < NMAP; ++mp) mx[mp] = fmax2(mx[mp], __shfl_xor(mx[mp], 16));
; #pragma unroll
;         for (int mp = 0; mp < NMAP; ++mp) mx[mp] = fmax2(mx[mp], __shfl_xor(mx[mp], 32));
; #pragma unroll
;         for (int mp = 0; mp < NMAP; ++mp) {
.LBB0_125:
	s_mov_b32 s15, s3
	s_add_i32 s3, s3, 1
	s_bitcmp1_b32 s3, 0
	s_cselect_b32 s14, 0x9000, 0
	v_add3_u32 v58, s14, v208, v209
	v_add3_u32 v59, s14, v210, v211
	s_waitcnt vmcnt(0)
	ds_write_b128 v58, v[86:89]
	ds_write_b128 v59, v[90:93]
	ds_write_b128 v58, v[98:101] offset:18432
	ds_write_b128 v59, v[102:105] offset:18432
	global_load_dwordx4 v[86:89], v236, s[34:35]
	global_load_dwordx4 v[90:93], v237, s[34:35]
	global_load_dwordx4 v[98:101], v238, s[34:35]
	global_load_dwordx4 v[102:105], v239, s[34:35]
	s_add_u32 s34, s34, 0x4000
	s_addc_u32 s35, s35, 0
	s_bitcmp1_b32 s15, 0
	s_cselect_b32 s15, 0x9000, 0
	v_add3_u32 v138, s15, v183, v182
	ds_read_b128 v[58:61], v138
	ds_read_b128 v[94:97], v138 offset:64
	ds_read_b128 v[114:117], v138 offset:4608
	ds_read_b128 v[118:121], v138 offset:4672
	ds_read_b128 v[122:125], v138 offset:9216
	ds_read_b128 v[126:129], v138 offset:9280
	ds_read_b128 v[130:133], v138 offset:13824
	ds_read_b128 v[134:137], v138 offset:13888
	s_waitcnt lgkmcnt(1)
	v_mfma_f32_16x16x32_bf16 v[58:61], v[58:61], v[14:17], v[106:109]
	v_mfma_f32_16x16x32_bf16 v[114:117], v[114:117], v[14:17], v[106:109]
	v_mfma_f32_16x16x32_bf16 v[122:125], v[122:125], v[14:17], v[106:109]
	v_mfma_f32_16x16x32_bf16 v[130:133], v[130:133], v[14:17], v[106:109]
	v_mfma_f32_16x16x32_bf16 v[154:157], v[94:97], v[10:13], v[58:61]
	v_mfma_f32_16x16x32_bf16 v[150:153], v[118:121], v[10:13], v[114:117]
	v_mfma_f32_16x16x32_bf16 v[146:149], v[126:129], v[10:13], v[122:125]
	s_waitcnt lgkmcnt(0)
	v_mfma_f32_16x16x32_bf16 v[94:97], v[134:137], v[10:13], v[130:133]
	ds_read_b128 v[58:61], v138 offset:128
	ds_read_b128 v[114:117], v138 offset:192
	ds_read_b128 v[118:121], v138 offset:4736
	ds_read_b128 v[122:125], v138 offset:4800
	ds_read_b128 v[126:129], v138 offset:9344
	ds_read_b128 v[130:133], v138 offset:9408
	ds_read_b128 v[134:137], v138 offset:13952
	ds_read_b128 v[212:215], v138 offset:14016
	s_waitcnt lgkmcnt(1)
	v_mfma_f32_16x16x32_bf16 v[58:61], v[58:61], v[6:9], v[110:113]
	v_mfma_f32_16x16x32_bf16 v[118:121], v[118:121], v[6:9], v[110:113]
	v_mfma_f32_16x16x32_bf16 v[142:145], v[114:117], v[2:5], v[58:61]
	v_max3_f32 v235, v154, v155, v156
	v_max3_f32 v235, v235, v157, v150
	v_max3_f32 v235, v235, v151, v152
	v_mfma_f32_16x16x32_bf16 v[126:129], v[126:129], v[6:9], v[110:113]
	v_max3_f32 v235, v235, v153, v146
	v_max3_f32 v235, v235, v147, v148
	v_mfma_f32_16x16x32_bf16 v[134:137], v[134:137], v[6:9], v[110:113]
	v_max3_f32 v235, v235, v149, v94
	v_max3_f32 v235, v235, v95, v96
	v_mfma_f32_16x16x32_bf16 v[138:141], v[122:125], v[2:5], v[118:121]
	v_max_f32_e32 v235, v235, v97
	v_mfma_f32_16x16x32_bf16 v[118:121], v[130:133], v[2:5], v[126:129]
	v_max3_f32 v59, v142, v143, v144
	s_waitcnt lgkmcnt(0)
	v_mfma_f32_16x16x32_bf16 v[114:117], v[212:215], v[2:5], v[134:137]
	v_add3_u32 v212, s15, v0, v181
	ds_read_b64_tr_b16 v[134:135], v212 offset:18432
	ds_read_b64_tr_b16 v[130:131], v212 offset:18464
	ds_read_b64_tr_b16 v[136:137], v212 offset:23040
	ds_read_b64_tr_b16 v[132:133], v212 offset:23072
	ds_read_b64_tr_b16 v[126:127], v212 offset:18496
	ds_read_b64_tr_b16 v[128:129], v212 offset:23104
	ds_read_b64_tr_b16 v[122:123], v212 offset:18528
	ds_read_b64_tr_b16 v[124:125], v212 offset:23136
	v_max3_f32 v59, v59, v145, v138
	v_max3_f32 v59, v59, v139, v140
	v_max3_f32 v59, v59, v141, v118
	v_max3_f32 v59, v59, v119, v120
	v_max3_f32 v59, v59, v121, v114
	v_max3_f32 v59, v59, v115, v116
	v_max_f32_e32 v225, v59, v117
	v_cmp_lt_f32_e32 vcc, s72, v235
	s_cbranch_vccz .LBB0_127
	ds_bpermute_b32 v60, v179, v235
	s_waitcnt lgkmcnt(0)
	v_max_f32_e32 v58, v235, v60
	ds_bpermute_b32 v60, v180, v58
	s_waitcnt lgkmcnt(0)
	v_max_f32_e32 v58, v58, v60
	v_max_f32_e32 v58, v58, v58
	v_max_f32_e32 v61, 0, v58
	v_exp_f32_e64 v60, -v61
	v_sub_f32_e32 v154, v154, v61
	v_sub_f32_e32 v155, v155, v61
	v_sub_f32_e32 v156, v156, v61
	v_pk_add_f32 v[58:59], v[166:167], v[60:61]
	v_pk_mul_f32 v[166:167], v[166:167], v[60:61]
	v_xor_b32_e32 v58, 0x80000000, v59
	v_mov_b32_e32 v167, v59
	v_sub_f32_e32 v157, v157, v61
	v_sub_f32_e32 v150, v150, v61
	v_sub_f32_e32 v151, v151, v61
	v_sub_f32_e32 v152, v152, v61
	v_sub_f32_e32 v153, v153, v61
	v_sub_f32_e32 v146, v146, v61
	v_sub_f32_e32 v147, v147, v61
	v_sub_f32_e32 v148, v148, v61
	v_sub_f32_e32 v149, v149, v61
	v_sub_f32_e32 v94, v94, v61
	v_sub_f32_e32 v95, v95, v61
	v_sub_f32_e32 v96, v96, v61
	v_sub_f32_e32 v97, v97, v61
	v_pk_mul_f32 v[80:81], v[80:81], v[60:61] op_sel_hi:[1,0]
	v_pk_mul_f32 v[78:79], v[78:79], v[60:61] op_sel_hi:[1,0]
	v_pk_mul_f32 v[76:77], v[76:77], v[60:61] op_sel_hi:[1,0]
	v_pk_mul_f32 v[74:75], v[74:75], v[60:61] op_sel_hi:[1,0]
	v_pk_mul_f32 v[68:69], v[68:69], v[60:61] op_sel_hi:[1,0]
	v_pk_mul_f32 v[66:67], v[66:67], v[60:61] op_sel_hi:[1,0]
	v_pk_mul_f32 v[56:57], v[56:57], v[60:61] op_sel_hi:[1,0]
	v_pk_mul_f32 v[54:55], v[54:55], v[60:61] op_sel_hi:[1,0]
	v_pk_mul_f32 v[48:49], v[48:49], v[60:61] op_sel_hi:[1,0]
	v_pk_mul_f32 v[46:47], v[46:47], v[60:61] op_sel_hi:[1,0]
	v_pk_mul_f32 v[40:41], v[40:41], v[60:61] op_sel_hi:[1,0]
	v_pk_mul_f32 v[38:39], v[38:39], v[60:61] op_sel_hi:[1,0]
	v_pk_mul_f32 v[32:33], v[32:33], v[60:61] op_sel_hi:[1,0]
	v_pk_mul_f32 v[30:31], v[30:31], v[60:61] op_sel_hi:[1,0]
	v_pk_mul_f32 v[24:25], v[24:25], v[60:61] op_sel_hi:[1,0]
	v_pk_mul_f32 v[22:23], v[22:23], v[60:61] op_sel_hi:[1,0]
	v_mov_b32_e32 v59, v58
	v_mov_b32_e32 v60, v58
	v_mov_b32_e32 v61, v58
	v_mov_b32_e32 v106, v58
	v_mov_b32_e32 v107, v58
	v_mov_b32_e32 v108, v58
	v_mov_b32_e32 v109, v58
	s_branch .LBB0_128
